# hand-written convert_weights phase: 34 loads in flight per wave instead of 2 (same math, same item set, different item order)
# speedup vs baseline: 1.0196x; 1.0196x over previous
; __device__ __forceinline__ void convert_weights(int wv, const Args& a, int l, LAS unsigned char* lds) {
;     const int tid = opaque_tid(wv), lane = tid & 63, wave = tid >> 6;
;     LAS float* scr = (LAS float*)(lds + wave * 16384);
;     unsigned char* ws = opaque_ptr(a.ws);
;     const int gw = blockIdx.x * 8 + wave, NGW = NWG * 8;
;     constexpr int I1 = 16 * 176, I1O = 44 * 32, IIN = 16 * 336, IA = 16 * 32, IB = 8 * 32, IO = 16 * 32;
;     constexpr int NIT = 2 * I1 + 2 * I1O + IIN + IA + IB + IO;
;     for (int it = gw; it < NIT; it += NGW) {
;         int r = it;
;         if (r < 2 * I1) {
;             const int which = r / I1; r -= which * I1;
;             const float* W = (which ? a.in[14] : a.in[2]) + (size_t)l * DM * 2 * DFF; const float* gn = (which ? a.in[13] : a.in[1]) + l * DM;
;             bf16_t* WT = (bf16_t*)(ws + (which ? W_2T : W_1T));
;             const int kb = r / 176, nb = r % 176, n0 = nb * 32, pn = n0 >> 8, bj = (n0 >> 7) & 1, i0 = n0 & 127;
;             transpose_item(W, DM, 2 * DFF, gn, WT, n0, bj * DFF + 128 * pn + i0, kb * 64, scr, lane); continue; }
;         r -= 2 * I1;
;         if (r < 2 * I1O) {
;             const int which = r / I1O; r -= which * I1O;
;             const float* W = (which ? a.in[15] : a.in[3]) + (size_t)l * DFF * DM; bf16_t* WT = (bf16_t*)(ws + (which ? W_2O : W_1O));
;             const int kb = r / 32, nb = r % 32;
;             transpose_item(W, DFF, DM, nullptr, WT, nb * 32, nb * 32, kb * 64, scr, lane); continue; }
;         r -= 2 * I1O;
;         if (r < IIN) { const float* W = a.in[5] + (size_t)l * DM * PIN; const float* gn = a.in[4] + l * DM; bf16_t* WT = (bf16_t*)(ws + W_IN);
;             const int kb = r / 336, nb = r % 336;
;             transpose_item(W, DM, PIN, gn, WT, nb * 32, nb * 32, kb * 64, scr, lane); continue; }
;         r -= IIN;
;         if (r < IA) { const float* W = a.in[10] + (size_t)l * DM * DM; bf16_t* WT = (bf16_t*)(ws + W_A); const int kb = r / 32, nb = r % 32;
;             transpose_item(W, DM, DM, nullptr, WT, nb * 32, nb * 32, kb * 64, scr, lane); continue; }
;         r -= IA;
;         if (r < IB) { const float* W = a.in[11] + (size_t)l * 512 * DM; bf16_t* WT = (bf16_t*)(ws + W_B); const int kb = r / 32, nb = r % 32;
;             transpose_item(W, 512, DM, nullptr, WT, nb * 32, nb * 32, kb * 64, scr, lane); continue; }
;         r -= IB;
.LBB0_41:
	v_readlane_b32 s0, v252, 4
	v_readlane_b32 s1, v252, 5
	s_mov_b64 exec, -1
	s_load_dwordx2 s[26:27], s[0:1], 0x88
	v_readlane_b32 s4, v252, 3
	v_readlane_b32 s5, v252, 1
	v_mbcnt_lo_u32_b32 v4, -1, 0
	v_mbcnt_hi_u32_b32 v4, -1, v4
	s_lshr_b32 s5, s5, 6
	s_add_u32 s4, s4, s5
	s_lshl_b32 s6, s5, 14
	v_and_b32_e32 v5, 31, v4
	v_lshrrev_b32_e32 v6, 5, v4
	v_lshlrev_b32_e32 v7, 2, v5
	v_and_b32_e32 v8, 7, v4
	v_lshrrev_b32_e32 v9, 3, v4
	v_mad_u32_u24 v10, v6, 33, v5
	v_lshl_add_u32 v10, v10, 2, s6
	v_mul_u32_u24_e32 v11, 0x108, v8
	v_add_u32_e32 v11, v11, v9
	v_lshl_add_u32 v11, v11, 2, s6
	v_lshlrev_b32_e32 v12, 5, v8
	v_lshlrev_b32_e32 v13, 4, v8
	s_waitcnt lgkmcnt(0)
	s_mov_b32 s22, s4
	s_cmpk_lt_u32 s22, 0x1600
	s_cbranch_scc0 .Lcvd_c2
	s_mov_b32 s40, 0x600000
	s_mov_b32 s29, 0x3080000
	s_cmpk_ge_u32 s22, 0xb00
	s_cselect_b32 s37, 0x70, 16
	s_cselect_b32 s36, 0x68, 8
	s_cselect_b32 s40, s29, s40
	s_cselect_b32 s29, 0xb00, 0
	s_sub_u32 s22, s22, s29
	s_movk_i32 s41, 0x1600
	s_movk_i32 s42, 0x400
	s_mov_b32 s39, 0x1600000
	s_mov_b32 s38, 1
	s_and_b32 s28, s22, 15
	s_bfe_u32 s23, s22, 0x40004
	s_lshr_b32 s29, s22, 8
	s_lshl_b32 s29, s29, 4
	s_add_u32 s28, s28, s29
	s_lshl_b32 s45, s28, 5
	s_lshr_b32 s29, s45, 8
	s_lshl_b32 s43, s29, 7
	s_and_b32 s29, s45, 0x7f
	s_add_u32 s43, s43, s29
	s_bitcmp1_b32 s45, 7
	s_cselect_b32 s29, 0xb00, 0
	s_add_u32 s43, s43, s29
	s_branch .Lcvd_done
.Lcvd_c2:
	s_sub_u32 s22, s22, 0x1600
	s_cmpk_lt_u32 s22, 0xb00
	s_cbranch_scc0 .Lcvd_c3
	s_mov_b32 s40, 0x1100000
	s_mov_b32 s29, 0x3b80000
	s_cmpk_ge_u32 s22, 0x580
	s_cselect_b32 s37, 0x78, 24
	s_cselect_b32 s40, s29, s40
	s_cselect_b32 s29, 0x580, 0
	s_sub_u32 s22, s22, s29
	s_movk_i32 s41, 0x400
	s_movk_i32 s42, 0xb00
	s_mov_b32 s39, 0xb00000
	s_mov_b32 s38, 0
	s_and_b32 s28, s22, 31
	s_lshr_b32 s23, s22, 5
	s_lshl_b32 s45, s28, 5
	s_mov_b32 s43, s45
	s_branch .Lcvd_done
.Lcvd_c3:
	s_sub_u32 s22, s22, 0xb00
	s_cmpk_lt_u32 s22, 0x1500
	s_cbranch_scc0 .Lcvd_c4
	s_movk_i32 s37, 0x28
	s_movk_i32 s36, 0x20
	s_mov_b32 s40, 0x1680000
	s_movk_i32 s41, 0x2a00
	s_movk_i32 s42, 0x400
	s_mov_b32 s39, 0x2a00000
	s_mov_b32 s38, 1
	s_and_b32 s28, s22, 15
	s_bfe_u32 s23, s22, 0x40004
	s_lshr_b32 s29, s22, 8
	s_lshl_b32 s29, s29, 4
	s_add_u32 s28, s28, s29
	s_lshl_b32 s45, s28, 5
	s_mov_b32 s43, s45
	s_branch .Lcvd_done
.Lcvd_c4:
	s_sub_u32 s22, s22, 0x1500
	s_movk_i32 s41, 0x400
	s_mov_b32 s38, 0
	s_cmpk_lt_u32 s22, 0x200
	s_cbranch_scc0 .Lcvd_c5
	s_movk_i32 s37, 0x50
	s_mov_b32 s40, 0x2b80000
	s_movk_i32 s42, 0x400
	s_mov_b32 s39, 0x400000
	s_branch .Lcvd_sq
.Lcvd_c5:
	s_sub_u32 s22, s22, 0x200
	s_cmpk_lt_u32 s22, 0x100
	s_cbranch_scc0 .Lcvd_c6
	s_movk_i32 s37, 0x58
	s_mov_b32 s40, 0x2d80000
	s_movk_i32 s42, 0x200
	s_mov_b32 s39, 0x200000
	s_branch .Lcvd_sq
.Lcvd_c6:
	s_sub_u32 s22, s22, 0x100
	s_movk_i32 s37, 0x60
	s_mov_b32 s40, 0x2e80000
	s_movk_i32 s42, 0x400
	s_mov_b32 s39, 0x400000
.Lcvd_sq:
	s_and_b32 s28, s22, 31
	s_lshr_b32 s23, s22, 5
	s_lshl_b32 s45, s28, 5
	s_mov_b32 s43, s45
.Lcvd_done:
	s_load_dwordx2 s[48:49], s[0:1], s37
	s_cmp_eq_u32 s38, 0
	s_cbranch_scc1 .Lcvd_nog
	s_load_dwordx2 s[50:51], s[0:1], s36
.Lcvd_nog:
	s_lshl_b32 s46, s23, 6
	s_mul_i32 s29, s46, s41
	s_add_u32 s29, s29, s43
	s_lshl_b32 s29, s29, 2
	s_mul_i32 s22, s44, s39
	s_add_u32 s29, s29, s22
	s_lshl_b32 s11, s41, 2
	s_lshl_b32 s10, s41, 3
	s_lshl_b32 s17, s42, 1
	s_lshl_b32 s16, s42, 4
	s_mul_i32 s22, s45, s42
	s_add_u32 s22, s22, s46
	s_lshl_b32 s22, s22, 1
	s_add_u32 s22, s22, s40
	s_add_u32 s14, s26, s22
	s_addc_u32 s15, s27, 0
	v_mad_u32_u24 v14, v6, s11, v7
	v_mad_u32_u24 v15, v9, s17, v13
	s_waitcnt lgkmcnt(0)
	s_add_u32 s8, s48, s29
	s_addc_u32 s9, s49, 0
	s_lshl_b32 s22, s44, 10
	s_add_u32 s22, s22, s46
	s_lshl_b32 s22, s22, 2
	s_add_u32 s12, s50, s22
	s_addc_u32 s13, s51, 0
	s_cmp_eq_u32 s38, 0
	s_cbranch_scc0 .Lcvd_hasg
	s_add_u32 s12, s26, 0x200000
	s_addc_u32 s13, s27, 0
; #define LAS __attribute__((address_space(3)))
; __device__ __forceinline__ void transpose_item(const float* W, int K, int Nsrc, const float* gain, bf16_t* WT, int dst_row0, int src_col0, int k0, LAS float* scr, int lane) {
; #pragma unroll 8
;     for (int i = 0; i < 32; ++i) { const int kk = 2 * i + (lane >> 5); const float g = gain ? gain[k0 + kk] : 1.f; scr[kk * 33 + (lane & 31)] = W[(size_t)(k0 + kk) * Nsrc + src_col0 + (lane & 31)] * g; }
;     asm volatile("s_waitcnt lgkmcnt(0)" ::: "memory");
; __device__ __forceinline__ void convert_weights(int wv, const Args& a, int l, LAS unsigned char* lds) {
;     ...
;     for (int it = gw; it < NIT; it += NGW) {
;         int r = it;
;         if (r < 2 * I1) {
;             const int which = r / I1; r -= which * I1;
;             const float* W = (which ? a.in[14] : a.in[2]) + (size_t)l * DM * 2 * DFF; const float* gn = (which ? a.in[13] : a.in[1]) + l * DM;
;             bf16_t* WT = (bf16_t*)(ws + (which ? W_2T : W_1T));
;             const int kb = r / 176, nb = r % 176, n0 = nb * 32, pn = n0 >> 8, bj = (n0 >> 7) & 1, i0 = n0 & 127;
;             transpose_item(W, DM, 2 * DFF, gn, WT, n0, bj * DFF + 128 * pn + i0, kb * 64, scr, lane); continue; }
.Lcvd_hasg:
	global_load_dword v72, v14, s[8:9]
	s_add_u32 s8, s8, s10
	s_addc_u32 s9, s9, 0
	global_load_dword v73, v14, s[8:9]
	s_add_u32 s8, s8, s10
	s_addc_u32 s9, s9, 0
	global_load_dword v74, v14, s[8:9]
	s_add_u32 s8, s8, s10
	s_addc_u32 s9, s9, 0
	global_load_dword v75, v14, s[8:9]
	s_add_u32 s8, s8, s10
	s_addc_u32 s9, s9, 0
	global_load_dword v76, v14, s[8:9]
	s_add_u32 s8, s8, s10
	s_addc_u32 s9, s9, 0
	global_load_dword v77, v14, s[8:9]
	s_add_u32 s8, s8, s10
	s_addc_u32 s9, s9, 0
	global_load_dword v78, v14, s[8:9]
	s_add_u32 s8, s8, s10
	s_addc_u32 s9, s9, 0
	global_load_dword v79, v14, s[8:9]
	s_add_u32 s8, s8, s10
	s_addc_u32 s9, s9, 0
	global_load_dword v80, v14, s[8:9]
	s_add_u32 s8, s8, s10
	s_addc_u32 s9, s9, 0
	global_load_dword v81, v14, s[8:9]
	s_add_u32 s8, s8, s10
	s_addc_u32 s9, s9, 0
	global_load_dword v82, v14, s[8:9]
	s_add_u32 s8, s8, s10
	s_addc_u32 s9, s9, 0
	global_load_dword v83, v14, s[8:9]
	s_add_u32 s8, s8, s10
	s_addc_u32 s9, s9, 0
	global_load_dword v84, v14, s[8:9]
	s_add_u32 s8, s8, s10
	s_addc_u32 s9, s9, 0
	global_load_dword v85, v14, s[8:9]
	s_add_u32 s8, s8, s10
	s_addc_u32 s9, s9, 0
	global_load_dword v86, v14, s[8:9]
	s_add_u32 s8, s8, s10
	s_addc_u32 s9, s9, 0
	global_load_dword v87, v14, s[8:9]
	s_add_u32 s8, s8, s10
	s_addc_u32 s9, s9, 0
	global_load_dword v88, v14, s[8:9]
	s_add_u32 s8, s8, s10
	s_addc_u32 s9, s9, 0
	global_load_dword v89, v14, s[8:9]
	s_add_u32 s8, s8, s10
	s_addc_u32 s9, s9, 0
	global_load_dword v90, v14, s[8:9]
	s_add_u32 s8, s8, s10
	s_addc_u32 s9, s9, 0
	global_load_dword v91, v14, s[8:9]
	s_add_u32 s8, s8, s10
	s_addc_u32 s9, s9, 0
	global_load_dword v92, v14, s[8:9]
	s_add_u32 s8, s8, s10
	s_addc_u32 s9, s9, 0
	global_load_dword v93, v14, s[8:9]
	s_add_u32 s8, s8, s10
	s_addc_u32 s9, s9, 0
	global_load_dword v94, v14, s[8:9]
	s_add_u32 s8, s8, s10
	s_addc_u32 s9, s9, 0
	global_load_dword v95, v14, s[8:9]
	s_add_u32 s8, s8, s10
	s_addc_u32 s9, s9, 0
	global_load_dword v96, v14, s[8:9]
	s_add_u32 s8, s8, s10
	s_addc_u32 s9, s9, 0
	global_load_dword v97, v14, s[8:9]
	s_add_u32 s8, s8, s10
	s_addc_u32 s9, s9, 0
	global_load_dword v98, v14, s[8:9]
	s_add_u32 s8, s8, s10
	s_addc_u32 s9, s9, 0
	global_load_dword v99, v14, s[8:9]
	s_add_u32 s8, s8, s10
	s_addc_u32 s9, s9, 0
	global_load_dword v100, v14, s[8:9]
	s_add_u32 s8, s8, s10
	s_addc_u32 s9, s9, 0
	global_load_dword v101, v14, s[8:9]
	s_add_u32 s8, s8, s10
	s_addc_u32 s9, s9, 0
	global_load_dword v102, v14, s[8:9]
	s_add_u32 s8, s8, s10
	s_addc_u32 s9, s9, 0
	global_load_dword v103, v14, s[8:9]
	global_load_dwordx4 v[20:23], v12, s[12:13]
	global_load_dwordx4 v[24:27], v12, s[12:13] offset:16
	s_mov_b64 s[18:19], s[14:15]
	s_mov_b32 s20, s16
	s_mov_b32 s21, s38
	v_mov_b32_e32 v16, v15
	s_waitcnt vmcnt(0)
.Lcv_loop:
	ds_write_b32 v10, v72 offset:0
	ds_write_b32 v10, v73 offset:264
	ds_write_b32 v10, v74 offset:528
	ds_write_b32 v10, v75 offset:792
	ds_write_b32 v10, v76 offset:1056
	ds_write_b32 v10, v77 offset:1320
	ds_write_b32 v10, v78 offset:1584
	ds_write_b32 v10, v79 offset:1848
	ds_write_b32 v10, v80 offset:2112
	ds_write_b32 v10, v81 offset:2376
	ds_write_b32 v10, v82 offset:2640
	ds_write_b32 v10, v83 offset:2904
	ds_write_b32 v10, v84 offset:3168
	ds_write_b32 v10, v85 offset:3432
	ds_write_b32 v10, v86 offset:3696
	ds_write_b32 v10, v87 offset:3960
	ds_write_b32 v10, v88 offset:4224
	ds_write_b32 v10, v89 offset:4488
	ds_write_b32 v10, v90 offset:4752
	ds_write_b32 v10, v91 offset:5016
	ds_write_b32 v10, v92 offset:5280
	ds_write_b32 v10, v93 offset:5544
	ds_write_b32 v10, v94 offset:5808
	ds_write_b32 v10, v95 offset:6072
	ds_write_b32 v10, v96 offset:6336
	ds_write_b32 v10, v97 offset:6600
	ds_write_b32 v10, v98 offset:6864
	ds_write_b32 v10, v99 offset:7128
	ds_write_b32 v10, v100 offset:7392
	ds_write_b32 v10, v101 offset:7656
	ds_write_b32 v10, v102 offset:7920
	ds_write_b32 v10, v103 offset:8184
	s_cmp_eq_u32 s21, 0
	s_cbranch_scc1 .Lcv_g1
	v_mov_b32_e32 v28, v20
	v_mov_b32_e32 v29, v21
	v_mov_b32_e32 v30, v22
	v_mov_b32_e32 v31, v23
	v_mov_b32_e32 v32, v24
	v_mov_b32_e32 v33, v25
	v_mov_b32_e32 v34, v26
	v_mov_b32_e32 v35, v27
	s_branch .Lcv_g2
.Lcv_g1:
	v_mov_b32_e32 v28, 1.0
	v_mov_b32_e32 v29, 1.0
	v_mov_b32_e32 v30, 1.0
	v_mov_b32_e32 v31, 1.0
	v_mov_b32_e32 v32, 1.0
	v_mov_b32_e32 v33, 1.0
	v_mov_b32_e32 v34, 1.0
	v_mov_b32_e32 v35, 1.0
.Lcv_g2:
	s_add_u32 s4, s4, 0x800
	s_cmpk_lt_u32 s4, 0x3b00
	s_cbranch_scc0 .Lcv_nonext
	s_mov_b32 s22, s4
	s_cmpk_lt_u32 s22, 0x1600
	s_cbranch_scc0 .Lcve_c2
	s_mov_b32 s40, 0x600000
	s_mov_b32 s29, 0x3080000
	s_cmpk_ge_u32 s22, 0xb00
	s_cselect_b32 s37, 0x70, 16
	s_cselect_b32 s36, 0x68, 8
	s_cselect_b32 s40, s29, s40
	s_cselect_b32 s29, 0xb00, 0
	s_sub_u32 s22, s22, s29
	s_movk_i32 s41, 0x1600
	s_movk_i32 s42, 0x400
	s_mov_b32 s39, 0x1600000
	s_mov_b32 s38, 1
	s_and_b32 s28, s22, 15
	s_bfe_u32 s23, s22, 0x40004
	s_lshr_b32 s29, s22, 8
	s_lshl_b32 s29, s29, 4
	s_add_u32 s28, s28, s29
	s_lshl_b32 s45, s28, 5
	s_lshr_b32 s29, s45, 8
	s_lshl_b32 s43, s29, 7
	s_and_b32 s29, s45, 0x7f
	s_add_u32 s43, s43, s29
	s_bitcmp1_b32 s45, 7
	s_cselect_b32 s29, 0xb00, 0
	s_add_u32 s43, s43, s29
	s_branch .Lcve_done

; #define LAS __attribute__((address_space(3)))
; __device__ __forceinline__ unsigned pk2(float lo, float hi) { f32x2 v = {lo, hi}; bf2_t b = __builtin_convertvector(v, bf2_t); return __builtin_bit_cast(unsigned, b); }
; __device__ __forceinline__ void transpose_item(const float* W, int K, int Nsrc, const float* gain, bf16_t* WT, int dst_row0, int src_col0, int k0, LAS float* scr, int lane) {
;     ...
;     const int c = lane & 7;
; #pragma unroll
;     for (int j = 0; j < 4; ++j) { const int n = (lane >> 3) + 8 * j; const LAS float* s = scr + (8 * c) * 33 + n;
;         u32x4 o; o.x = pk2(s[0 * 33], s[1 * 33]); o.y = pk2(s[2 * 33], s[3 * 33]); o.z = pk2(s[4 * 33], s[5 * 33]); o.w = pk2(s[6 * 33], s[7 * 33]);
;         *(u32x4*)(WT + (size_t)(dst_row0 + n) * K + k0 + 8 * c) = o; }
;     asm volatile("s_waitcnt lgkmcnt(0)" ::: "memory");
.Lcve_hasg:
	global_load_dword v72, v14, s[8:9]
	s_add_u32 s8, s8, s10
	s_addc_u32 s9, s9, 0
	global_load_dword v73, v14, s[8:9]
	s_add_u32 s8, s8, s10
	s_addc_u32 s9, s9, 0
	global_load_dword v74, v14, s[8:9]
	s_add_u32 s8, s8, s10
	s_addc_u32 s9, s9, 0
	global_load_dword v75, v14, s[8:9]
	s_add_u32 s8, s8, s10
	s_addc_u32 s9, s9, 0
	global_load_dword v76, v14, s[8:9]
	s_add_u32 s8, s8, s10
	s_addc_u32 s9, s9, 0
	global_load_dword v77, v14, s[8:9]
	s_add_u32 s8, s8, s10
	s_addc_u32 s9, s9, 0
	global_load_dword v78, v14, s[8:9]
	s_add_u32 s8, s8, s10
	s_addc_u32 s9, s9, 0
	global_load_dword v79, v14, s[8:9]
	s_add_u32 s8, s8, s10
	s_addc_u32 s9, s9, 0
	global_load_dword v80, v14, s[8:9]
	s_add_u32 s8, s8, s10
	s_addc_u32 s9, s9, 0
	global_load_dword v81, v14, s[8:9]
	s_add_u32 s8, s8, s10
	s_addc_u32 s9, s9, 0
	global_load_dword v82, v14, s[8:9]
	s_add_u32 s8, s8, s10
	s_addc_u32 s9, s9, 0
	global_load_dword v83, v14, s[8:9]
	s_add_u32 s8, s8, s10
	s_addc_u32 s9, s9, 0
	global_load_dword v84, v14, s[8:9]
	s_add_u32 s8, s8, s10
	s_addc_u32 s9, s9, 0
	global_load_dword v85, v14, s[8:9]
	s_add_u32 s8, s8, s10
	s_addc_u32 s9, s9, 0
	global_load_dword v86, v14, s[8:9]
	s_add_u32 s8, s8, s10
	s_addc_u32 s9, s9, 0
	global_load_dword v87, v14, s[8:9]
	s_add_u32 s8, s8, s10
	s_addc_u32 s9, s9, 0
	global_load_dword v88, v14, s[8:9]
	s_add_u32 s8, s8, s10
	s_addc_u32 s9, s9, 0
	global_load_dword v89, v14, s[8:9]
	s_add_u32 s8, s8, s10
	s_addc_u32 s9, s9, 0
	global_load_dword v90, v14, s[8:9]
	s_add_u32 s8, s8, s10
	s_addc_u32 s9, s9, 0
	global_load_dword v91, v14, s[8:9]
	s_add_u32 s8, s8, s10
	s_addc_u32 s9, s9, 0
	global_load_dword v92, v14, s[8:9]
	s_add_u32 s8, s8, s10
	s_addc_u32 s9, s9, 0
	global_load_dword v93, v14, s[8:9]
	s_add_u32 s8, s8, s10
	s_addc_u32 s9, s9, 0
	global_load_dword v94, v14, s[8:9]
	s_add_u32 s8, s8, s10
	s_addc_u32 s9, s9, 0
	global_load_dword v95, v14, s[8:9]
	s_add_u32 s8, s8, s10
	s_addc_u32 s9, s9, 0
	global_load_dword v96, v14, s[8:9]
	s_add_u32 s8, s8, s10
	s_addc_u32 s9, s9, 0
	global_load_dword v97, v14, s[8:9]
	s_add_u32 s8, s8, s10
	s_addc_u32 s9, s9, 0
	global_load_dword v98, v14, s[8:9]
	s_add_u32 s8, s8, s10
	s_addc_u32 s9, s9, 0
	global_load_dword v99, v14, s[8:9]
	s_add_u32 s8, s8, s10
	s_addc_u32 s9, s9, 0
	global_load_dword v100, v14, s[8:9]
	s_add_u32 s8, s8, s10
	s_addc_u32 s9, s9, 0
	global_load_dword v101, v14, s[8:9]
	s_add_u32 s8, s8, s10
	s_addc_u32 s9, s9, 0
	global_load_dword v102, v14, s[8:9]
	s_add_u32 s8, s8, s10
	s_addc_u32 s9, s9, 0
	global_load_dword v103, v14, s[8:9]
	global_load_dwordx4 v[20:23], v12, s[12:13]
	global_load_dwordx4 v[24:27], v12, s[12:13] offset:16
.Lcv_nonext:
	s_waitcnt lgkmcnt(0)
	ds_read_b32 v104, v11 offset:0
	ds_read_b32 v105, v11 offset:132
	ds_read_b32 v106, v11 offset:264
	ds_read_b32 v107, v11 offset:396
	ds_read_b32 v108, v11 offset:528
	ds_read_b32 v109, v11 offset:660
	ds_read_b32 v110, v11 offset:792
	ds_read_b32 v111, v11 offset:924
	ds_read_b32 v112, v11 offset:32
	ds_read_b32 v113, v11 offset:164
	ds_read_b32 v114, v11 offset:296
	ds_read_b32 v115, v11 offset:428
	ds_read_b32 v116, v11 offset:560
	ds_read_b32 v117, v11 offset:692
	ds_read_b32 v118, v11 offset:824
	ds_read_b32 v119, v11 offset:956
	s_waitcnt lgkmcnt(8)
	v_mul_f32_e32 v104, v104, v28
	v_mul_f32_e32 v105, v105, v29
	v_mul_f32_e32 v106, v106, v30
	v_mul_f32_e32 v107, v107, v31
	v_mul_f32_e32 v108, v108, v32
	v_mul_f32_e32 v109, v109, v33
	v_mul_f32_e32 v110, v110, v34
	v_mul_f32_e32 v111, v111, v35
	v_cvt_pk_bf16_f32 v136, v104, v105
	v_cvt_pk_bf16_f32 v137, v106, v107
	v_cvt_pk_bf16_f32 v138, v108, v109
	v_cvt_pk_bf16_f32 v139, v110, v111
	global_store_dwordx4 v16, v[136:139], s[18:19]
	s_add_u32 s18, s18, s20
	s_addc_u32 s19, s19, 0
	ds_read_b32 v120, v11 offset:64
	ds_read_b32 v121, v11 offset:196
	ds_read_b32 v122, v11 offset:328
	ds_read_b32 v123, v11 offset:460
	ds_read_b32 v124, v11 offset:592
	ds_read_b32 v125, v11 offset:724
	ds_read_b32 v126, v11 offset:856
	ds_read_b32 v127, v11 offset:988
	s_waitcnt lgkmcnt(8)
	v_mul_f32_e32 v112, v112, v28
	v_mul_f32_e32 v113, v113, v29
	v_mul_f32_e32 v114, v114, v30
	v_mul_f32_e32 v115, v115, v31
	v_mul_f32_e32 v116, v116, v32
	v_mul_f32_e32 v117, v117, v33
	v_mul_f32_e32 v118, v118, v34
	v_mul_f32_e32 v119, v119, v35
	v_cvt_pk_bf16_f32 v140, v112, v113
	v_cvt_pk_bf16_f32 v141, v114, v115
	v_cvt_pk_bf16_f32 v142, v116, v117
	v_cvt_pk_bf16_f32 v143, v118, v119
	global_store_dwordx4 v16, v[140:143], s[18:19]
	s_add_u32 s18, s18, s20
	s_addc_u32 s19, s19, 0
	ds_read_b32 v128, v11 offset:96
	ds_read_b32 v129, v11 offset:228
	ds_read_b32 v130, v11 offset:360
	ds_read_b32 v131, v11 offset:492
	ds_read_b32 v132, v11 offset:624
	ds_read_b32 v133, v11 offset:756
	ds_read_b32 v134, v11 offset:888
	ds_read_b32 v135, v11 offset:1020
	s_waitcnt lgkmcnt(8)
	v_mul_f32_e32 v120, v120, v28
	v_mul_f32_e32 v121, v121, v29
	v_mul_f32_e32 v122, v122, v30
	v_mul_f32_e32 v123, v123, v31
	v_mul_f32_e32 v124, v124, v32
	v_mul_f32_e32 v125, v125, v33
	v_mul_f32_e32 v126, v126, v34
	v_mul_f32_e32 v127, v127, v35
	v_cvt_pk_bf16_f32 v144, v120, v121
	v_cvt_pk_bf16_f32 v145, v122, v123
	v_cvt_pk_bf16_f32 v146, v124, v125
	v_cvt_pk_bf16_f32 v147, v126, v127
	global_store_dwordx4 v16, v[144:147], s[18:19]
	s_add_u32 s18, s18, s20
	s_addc_u32 s19, s19, 0
	s_waitcnt lgkmcnt(0)
	v_mul_f32_e32 v128, v128, v28
	v_mul_f32_e32 v129, v129, v29
	v_mul_f32_e32 v130, v130, v30
	v_mul_f32_e32 v131, v131, v31
	v_mul_f32_e32 v132, v132, v32
	v_mul_f32_e32 v133, v133, v33
	v_mul_f32_e32 v134, v134, v34
	v_mul_f32_e32 v135, v135, v35
	v_cvt_pk_bf16_f32 v148, v128, v129
	v_cvt_pk_bf16_f32 v149, v130, v131
	v_cvt_pk_bf16_f32 v150, v132, v133
	v_cvt_pk_bf16_f32 v151, v134, v135
	global_store_dwordx4 v16, v[148:151], s[18:19]
	s_cmpk_lt_u32 s4, 0x3b00
	s_cbranch_scc0 .Lcv_end
	s_mov_b64 s[18:19], s[14:15]
	s_mov_b32 s20, s16
	s_mov_b32 s21, s38
	v_mov_b32_e32 v16, v15
	s_waitcnt vmcnt(4)
	s_branch .Lcv_loop
.Lcv_end:
	s_lshl_b32 s34, s44, 10
	s_mov_b32 s35, s73
.LBB0_108:
	s_xor_b64 s[0:1], s[24:25], -1
	v_writelane_b32 v253, s0, 34
	v_mbcnt_lo_u32_b32 v0, -1, 0
	v_mbcnt_hi_u32_b32 v0, -1, v0
	s_nop 1
	v_writelane_b32 v253, s1, 35
	s_xor_b64 s[0:1], s[2:3], -1
	v_writelane_b32 v253, s0, 36
	s_nop 1
	v_writelane_b32 v253, s1, 37
	v_readlane_b32 s0, v252, 1
	s_nop 1
	v_or_b32_e32 v0, s0, v0
	v_readlane_b32 s0, v252, 2
	s_nop 1
	v_add_u32_e32 v0, s0, v0
	s_mov_b32 s0, 0xc0000
	v_cmp_gt_i32_e32 vcc, s0, v0
	s_and_saveexec_b64 s[0:1], vcc
	s_xor_b64 s[0:1], exec, s[0:1]
	s_cbranch_execz .LBB0_117
	v_max_i32_e32 v1, 0xa0000, v0
	v_sub_u32_e32 v1, v1, v0
	s_add_u32 s2, s26, 0x1e100000
	v_add_u32_e32 v1, 0x1ffff, v1
	s_mov_b32 s4, 0x1ffff
	s_addc_u32 s3, s27, 0
	v_cmp_lt_u32_e32 vcc, s4, v1
	s_mov_b64 s[6:7], -1
	s_and_saveexec_b64 s[4:5], vcc
	s_cbranch_execz .LBB0_113
	v_lshrrev_b32_e32 v1, 17, v1
	v_add_u32_e32 v4, 1, v1
	v_and_b32_e32 v5, 0xfffe, v4
	v_add_u32_e32 v1, 0x20000, v0
	s_mov_b64 s[6:7], 0
	v_mov_b32_e32 v6, v5
	v_mov_b64_e32 v[2:3], v[0:1]
